# attention V staging: V tile row-major in LDS (two 16-byte LDS stores per thread) read with the hardware transpose read as the P.V operand, replacing 16 two-byte transposing LDS stores per thread and t
# speedup vs baseline: 1.0311x; 1.0121x over previous
; __device__ void attn_item(const Params& p, int s_idx, char* smem) {
;     const int qb = 63 - (s_idx >> 5), bh = s_idx & 31, b = bh >> 3, h = bh & 7;
;     const int tid = get_tid(), lane = tid & 63, wid = tid >> 6, ql = lane & 31, hh = lane >> 5;
;     const int qrow = qb * 128 + wid * 32 + ql;
;     const bf16_t* projb = p.proj + (size_t)b * S * NIN;
;     bf16x8 qf[4];
; #pragma unroll
;     for (int kk = 0; kk < 4; ++kk) qf[kk] = *(const bf16x8*)(projb + (size_t)qrow * NIN + h * 64 + kk * 16 + hh * 8);
;     f32x16 O0, O1;
; #pragma unroll
;     for (int i = 0; i < 16; ++i) { O0[i] = 0.f; O1[i] = 0.f; }
;     float mrun = -INFINITY, lsum = 0.f;
;     const int nkt = qb * 2 + 2;
;     const int wave_last = (qb * 128 + wid * 32 + 31) >> 6;
;     const int wave_q0 = qb * 128 + wid * 32;
;     const float sc = 0.125f * LOG2E;
;     struct KV { u32x4 rk[2], rv[2]; float rkb; };
;     KV sa;
;     auto gload = [&](int kt, KV& st) {
; #pragma unroll
;         for (int i = 0; i < 2; ++i) {
;             const int c = tid + 256 * i, key = c >> 3, dc = c & 7;
;             const bf16_t* src = projb + (size_t)(kt * 64 + key) * NIN + h * 64 + dc * 8;
;             st.rk[i] = *(const u32x4*)(src + 512);
;             const int keyv = c & 63, dcv = c >> 6;
;             st.rv[i] = *(const u32x4*)(projb + (size_t)(kt * 64 + keyv) * NIN + 1024 + h * 64 + dcv * 8);
;         }
;         st.rkb = p.kb[(size_t)bh * S + kt * 64 + (tid & 63)];
;     };
;     auto sstore = [&](int buf, const KV& st) {
;         bf16_t* sK = (bf16_t*)(smem + buf * ATT_BUF); bf16_t* sVt = sK + 64 * 72; float* sKb = (float*)(smem + buf * ATT_BUF + 18432);
; #pragma unroll
;         for (int i = 0; i < 2; ++i) {
;             const int c = tid + 256 * i, key = c >> 3, dc = c & 7;
;             *(u32x4*)(sK + key * 72 + dc * 8) = st.rk[i];
;             const unsigned w0 = st.rv[i].x, w1 = st.rv[i].y, w2 = st.rv[i].z, w3 = st.rv[i].w;
;             bf16_t* d = sVt + ((c >> 6) * 8) * 72 + (c & 63);
;             d[0 * 72] = (bf16_t)(w0 & 0xffffu); d[1 * 72] = (bf16_t)(w0 >> 16);
;             d[2 * 72] = (bf16_t)(w1 & 0xffffu); d[3 * 72] = (bf16_t)(w1 >> 16);
;             d[4 * 72] = (bf16_t)(w2 & 0xffffu); d[5 * 72] = (bf16_t)(w2 >> 16);
;             d[6 * 72] = (bf16_t)(w3 & 0xffffu); d[7 * 72] = (bf16_t)(w3 >> 16);
;         }
;         if (tid < 64) sKb[tid] = st.rkb;
.LBB0_107:
	s_ashr_i32 s12, s15, 5
	s_lshl_b32 s13, s15, 10
	s_sub_i32 s14, 63, s12
	v_mov_b32_e32 v3, v126
	s_and_b32 s13, s13, 0x6000
	s_and_b32 s18, s15, 31
	s_lshl_b32 s12, s14, 7
	v_ashrrev_i32_e32 v143, 6, v3
	s_mul_i32 s16, s13, 0x1410
	v_lshlrev_b32_e32 v96, 5, v143
	s_add_u32 s34, s90, s16
	v_and_b32_e32 v2, 31, v3
	v_add_u32_e32 v144, s12, v96
	s_addc_u32 s35, s91, 0
	s_lshl_b32 s15, s15, 6
	v_or_b32_e32 v98, v144, v2
	s_waitcnt lgkmcnt(0)
	v_mov_b64_e32 v[0:1], s[34:35]
	s_and_b32 s15, s15, 0x1c0
	v_bfe_u32 v4, v3, 5, 1
	v_mad_i64_i32 v[6:7], s[16:17], v98, s29, v[0:1]
	s_lshl_b32 s22, s15, 1
	s_mov_b32 s23, s21
	v_lshl_add_u64 v[6:7], v[6:7], 0, s[22:23]
	v_lshlrev_b32_e32 v112, 4, v4
	v_lshl_add_u64 v[6:7], v[6:7], 0, v[112:113]
	v_ashrrev_i32_e32 v145, 3, v3
	v_lshlrev_b32_e32 v5, 3, v3
	global_load_dwordx4 v[64:67], v[6:7], off
	global_load_dwordx4 v[68:71], v[6:7], off offset:32
	global_load_dwordx4 v[72:75], v[6:7], off offset:64
	global_load_dwordx4 v[76:79], v[6:7], off offset:96
	v_readlane_b32 s98, v165, 2
	v_readlane_b32 s99, v165, 3
	v_readlane_b32 s32, v167, 36
	v_and_b32_e32 v32, 7, v130
	v_bfe_u32 v33, v130, 3, 1
	v_lshlrev_b32_e32 v32, 7, v32
	s_mul_i32 s32, s32, 0xc00
	v_lshl_or_b32 v32, v33, 10, v32
	v_mov_b32_e32 v33, s18
	s_add_i32 s32, s32, 32
	v_and_b32_e32 v33, 7, v33
	v_add_u32_e32 v32, s32, v32
	v_lshl_add_u32 v32, v33, 2, v32
	global_load_dword v34, v32, s[98:99] sc0 sc1
	s_lshl_b32 s32, s18, 15
	v_lshlrev_b32_e32 v35, 8, v130
	v_add_u32_e32 v35, s32, v35
	v_add_u32_e32 v38, 0x4000, v35
	s_lshl_b32 s32, s14, 9
	v_add_u32_e32 v39, s32, v35
	v_lshlrev_b32_e32 v33, 8, v130
	v_sub_u32_e32 v39, v39, v33
	v_readlane_b32 s98, v165, 40
	v_readlane_b32 s99, v165, 41
	s_nop 4
	s_nop 0
	global_load_dword v36, v35, s[98:99] offset:252
	global_load_dword v37, v38, s[98:99] offset:252
	global_load_dword v39, v39, s[98:99]
	s_waitcnt vmcnt(3)
	v_max_u32_dpp v34, v34, v34 quad_perm:[1,0,3,2] row_mask:0xf bank_mask:0xf
	s_nop 1
	v_max_u32_dpp v34, v34, v34 quad_perm:[2,3,0,1] row_mask:0xf bank_mask:0xf
	s_nop 1
	v_max_u32_dpp v34, v34, v34 row_half_mirror row_mask:0xf bank_mask:0xf
	s_waitcnt vmcnt(0)
	s_nop 0
	v_readlane_b32 s98, v34, 0
	v_readlane_b32 s99, v34, 8
	v_mov_b32_e32 v41, 0xbebae186
	s_nop 0
	v_mov_b32_e32 v40, s98
	v_mul_f32_e32 v40, s99, v40
	v_sqrt_f32_e32 v40, v40
	s_nop 0
	v_fma_f32 v40, v40, v41, v39
	v_add_f32_e32 v40, 0xc31b0000, v40
	v_cmp_lt_f32_e32 vcc, v36, v40
	s_bcnt1_i32_b64 s32, vcc
	v_cmp_lt_f32_e32 vcc, v37, v40
	s_bcnt1_i32_b64 s98, vcc
	s_add_i32 s32, s32, s98
	s_lshl_b32 s98, s14, 1
	s_min_i32 s32, s32, s98
	s_and_b32 s32, s32, -2
	s_lshl_b32 s98, s32, 6
	s_lshl_b32 s99, s14, 7
	s_add_i32 s99, s99, 64
	s_mul_i32 s99, s99, 0x1410
	s_add_u32 s34, s34, s99
	s_addc_u32 s35, s35, 0
	s_lshl_b32 s99, s14, 1
	s_add_i32 s99, s99, 1
	s_sub_i32 s99, s99, s32
	s_lshl_b32 s99, s99, 6
	v_subrev_u32_e32 v98, s98, v98
	v_subrev_u32_e32 v144, s98, v144
	v_mov_b64_e32 v[0:1], s[34:35]
	v_mad_i64_i32 v[6:7], s[16:17], v145, s29, v[0:1]
	v_and_b32_e32 v5, 56, v5
	v_lshl_add_u64 v[6:7], v[6:7], 0, s[22:23]
	v_lshlrev_b32_e32 v112, 1, v5
	v_lshl_add_u64 v[6:7], v[6:7], 0, v[112:113]
	global_load_dwordx4 v[6:9], v[6:7], off offset:1024
	v_add_u32_e32 v5, 0x100, v3
	v_and_b32_e32 v114, 63, v3
	v_ashrrev_i32_e32 v146, 3, v5
	v_lshrrev_b32_e32 v135, 2, v3
	v_and_b32_e32 v10, 15, v3
	v_mul_u32_u24_e32 v10, 0x1410, v135
	v_mov_b32_e32 v11, v113
	v_mad_i64_i32 v[0:1], s[16:17], v146, s29, v[0:1]
	v_readlane_b32 s48, v165, 26
	v_lshl_add_u64 v[10:11], s[34:35], 0, v[10:11]
	v_and_b32_e32 v100, 3, v3
	v_lshlrev_b32_e32 v100, 3, v100
	v_lshl_add_u64 v[0:1], v[0:1], 0, s[22:23]
	v_add_u32_e32 v102, 32, v100
	s_lshl_b32 s15, s18, 15
	v_readlane_b32 s62, v165, 40
	v_lshl_add_u64 v[14:15], v[10:11], 0, s[22:23]
	v_ashrrev_i32_e32 v101, 31, v100
	v_lshl_add_u64 v[0:1], v[0:1], 0, v[112:113]
	v_ashrrev_i32_e32 v103, 31, v102
	v_readlane_b32 s63, v165, 41
	s_add_u32 s16, s62, s15
	v_lshl_add_u64 v[16:17], v[100:101], 1, v[14:15]
	global_load_dwordx4 v[10:13], v[0:1], off offset:1024
	v_lshl_add_u64 v[0:1], v[102:103], 1, v[14:15]
	s_addc_u32 s17, s63, 0
	s_lshl_b32 s98, s98, 2
	s_add_u32 s16, s16, s98
	s_addc_u32 s17, s17, 0
	v_lshlrev_b32_e32 v14, 2, v114
	v_mov_b32_e32 v15, v113
	s_movk_i32 s15, 0x90
	v_lshl_add_u64 v[104:105], s[16:17], 0, v[14:15]
	v_mad_u64_u32 v[106:107], s[16:17], v145, s15, v[112:113]
	v_mul_lo_u32 v5, v100, s15
	v_lshlrev_b32_e32 v14, 1, v135
	v_lshlrev_b32_e32 v107, 4, v126
	v_mad_u64_u32 v[108:109], s[16:17], v146, s15, v[112:113]
	v_mul_lo_u32 v5, v102, s15
	s_movk_i32 s44, 0x90
	v_add_u32_e32 v109, 0x1000, v107
	v_cmp_gt_i32_e64 s[40:41], 64, v3
	v_lshlrev_b32_e32 v147, 2, v3
	v_readlane_b32 s49, v165, 27
	v_readlane_b32 s50, v165, 28
	v_readlane_b32 s51, v165, 29
	v_readlane_b32 s52, v165, 30
	v_readlane_b32 s53, v165, 31
	v_readlane_b32 s54, v165, 32
	v_readlane_b32 s55, v165, 33
	v_readlane_b32 s56, v165, 34
	v_readlane_b32 s57, v165, 35
	v_readlane_b32 s58, v165, 36
	v_readlane_b32 s59, v165, 37
	v_readlane_b32 s60, v165, 38
	v_readlane_b32 s61, v165, 39
	s_waitcnt vmcnt(1)
	ds_write_b128 v106, v[6:9]
	global_load_dwordx4 v[6:9], v[16:17], off offset:2048
	s_waitcnt vmcnt(0)
	ds_write_b128 v107, v[6:9] offset:9216
	global_load_dwordx4 v[6:9], v[0:1], off offset:2048
	ds_write_b128 v108, v[10:13]
	s_waitcnt vmcnt(0)
	ds_write_b128 v109, v[6:9] offset:9216
	s_and_saveexec_b64 s[24:25], s[40:41]
	s_cbranch_execz .LBB0_109
	v_mov_b32_e32 v0, s99
	v_lshlrev_b32_e32 v0, 2, v0
	v_mov_b32_e32 v1, 0
	v_lshl_add_u64 v[0:1], v[104:105], 0, v[0:1]
	global_load_dword v0, v[0:1], off
	s_waitcnt vmcnt(0)
	ds_write_b32 v147, v0 offset:18432
; __device__ void attn_item(const Params& p, int s_idx, char* smem) {
;     ...
;     f32x16 O0, O1;
; #pragma unroll
;     for (int i = 0; i < 16; ++i) { O0[i] = 0.f; O1[i] = 0.f; }
;     float mrun = -INFINITY, lsum = 0.f;
;     ...
;     const int pr = (ql & 0x13) | ((ql & 4) << 1) | ((ql & 8) >> 1);
;     auto compute = [&](int kt, int buf) {
;         if (kt <= wave_last) {
;             const bf16_t* sK = (const bf16_t*)(smem + buf * ATT_BUF); const bf16_t* sVt = sK + 64 * 72; const float* sKb = (const float*)(smem + buf * ATT_BUF + 18432);
;             f32x16 S0, S1;
; #pragma unroll
;             for (int i = 0; i < 16; ++i) { S0[i] = 0.f; S1[i] = 0.f; }
; #pragma unroll
;             for (int kk = 0; kk < 4; ++kk) {
;                 const bf16x8 k0 = *(const bf16x8*)(sK + pr * 72 + kk * 16 + hh * 8);
;                 const bf16x8 k1 = *(const bf16x8*)(sK + (32 + pr) * 72 + kk * 16 + hh * 8);
.LBB0_109:
	s_or_b64 exec, exec, s[24:25]
	v_and_b32_e32 v0, 19, v3
	v_lshlrev_b32_e32 v1, 1, v2
	v_lshrrev_b32_e32 v3, 1, v3
	v_and_b32_e32 v1, 8, v1
	v_and_b32_e32 v3, 4, v3
	v_lshlrev_b32_e32 v141, 3, v4
	s_lshl_b32 s14, s14, 1
	v_or3_b32 v0, v3, v0, v1
	s_mul_i32 s98, s99, 0x1410
	s_sub_u32 s34, s34, s98
	s_subb_u32 s35, s35, 0
	s_add_u32 s34, s34, s22
	v_mul_u32_u24_e32 v0, 0x48, v0
	v_lshlrev_b32_e32 v1, 1, v141
	v_mul_u32_u24_e32 v148, 0x48, v2
	v_mov_b32_e32 v14, v113
	v_mov_b32_e32 v15, v113
	s_addc_u32 s35, s35, 0
	v_lshl_add_u32 v150, v0, 1, v1
	v_lshrrev_b32_e32 v152, 5, v130
	v_lshlrev_b32_e32 v152, 9, v152
	v_bfe_u32 v0, v130, 2, 2
	v_lshl_or_b32 v152, v0, 6, v152
	v_bfe_u32 v0, v130, 4, 1
	v_lshl_or_b32 v152, v0, 5, v152
	v_and_b32_e32 v0, 3, v130
	v_lshl_or_b32 v152, v0, 3, v152
	s_mov_b32 s20, 0
	v_mov_b32_e32 v0, v113
	v_mov_b32_e32 v1, v113
	v_mov_b32_e32 v2, v113
	v_mov_b32_e32 v3, v113
	v_mov_b32_e32 v4, v113
	v_mov_b32_e32 v5, v113
	v_mov_b32_e32 v6, v113
	v_mov_b32_e32 v7, v113
	v_mov_b32_e32 v8, v113
	v_mov_b32_e32 v9, v113
	v_mov_b32_e32 v10, v113
	v_mov_b32_e32 v11, v113
	v_mov_b32_e32 v12, v113
	v_mov_b32_e32 v13, v113
	v_mov_b64_e32 v[30:31], v[14:15]
	v_ashrrev_i32_e32 v149, 6, v144
	v_lshl_add_u64 v[110:111], s[34:35], 0, v[112:113]
	v_lshlrev_b32_e32 v151, 2, v141
	s_or_b32 s15, s14, 1
	s_sub_i32 s14, s14, s32
	s_sub_i32 s15, s15, s32
	v_mov_b32_e32 v97, v98
	v_mov_b32_e32 v99, v98
	v_add_u32_e32 v153, 0xffffffc0, v146
	v_add_u32_e32 v154, 0xffffffc0, v135
	v_add_u32_e32 v155, 0xffffffc0, v145
	v_mov_b32_e32 v157, 0xff800000
	v_mov_b32_e32 v156, 0
	s_mov_b32 s16, s15
	s_lshl_b32 s20, s15, 6
	v_add_u32_e32 v127, s20, v155
	v_add_u32_e32 v128, s20, v153
	v_add_u32_e32 v129, s20, v154
	v_mul_lo_u32 v127, v127, s29
	v_mul_lo_u32 v128, v128, s29
	v_mul_lo_u32 v129, v129, s29
	v_add_u32_e32 v127, v127, v112
	v_add_u32_e32 v128, v128, v112
	v_lshl_add_u32 v131, v102, 1, v129
	v_lshl_add_u32 v129, v100, 1, v129
	v_mov_b64_e32 v[28:29], v[12:13]
	v_mov_b64_e32 v[26:27], v[10:11]
	v_mov_b64_e32 v[24:25], v[8:9]
	v_mov_b64_e32 v[22:23], v[6:7]
	v_mov_b64_e32 v[20:21], v[4:5]
	v_mov_b64_e32 v[18:19], v[2:3]
	v_mov_b64_e32 v[16:17], v[0:1]
	s_waitcnt lgkmcnt(0)
	s_barrier

; __device__ __forceinline__ unsigned pk_bf16(float lo, float hi) { unsigned r; asm("v_cvt_pk_bf16_f32 %0, %1, %2" : "=v"(r) : "v"(lo), "v"(hi)); return r; }
; __device__ void attn_item(const Params& p, int s_idx, char* smem) {
;     ...
;             float mx = sv[0];
; #pragma unroll
;             for (int i = 1; i < 32; ++i) mx = fmaxf(mx, sv[i]);
;             mx = fmaxf(mx, __shfl_xor(mx, 32));
;             const float mnew = fmaxf(mrun, mx);
;             const float alpha = __builtin_amdgcn_exp2f(mrun - mnew);
;             mrun = mnew;
;             float psum = 0.f;
; #pragma unroll
;             for (int i = 0; i < 32; ++i) { sv[i] = __builtin_amdgcn_exp2f(sv[i] - mnew); psum += sv[i]; }
;             lsum = lsum * alpha + psum;
; #pragma unroll
;             for (int i = 0; i < 16; ++i) { O0[i] *= alpha; O1[i] *= alpha; }
; #pragma unroll
;             for (int g = 0; g < 4; ++g) {
;                 bf16x8 pf;
;                 {
;                     const unsigned u0 = pk_bf16(sv[g * 8 + 0], sv[g * 8 + 1]), u1 = pk_bf16(sv[g * 8 + 2], sv[g * 8 + 3]);
;                     const unsigned u2 = pk_bf16(sv[g * 8 + 4], sv[g * 8 + 5]), u3 = pk_bf16(sv[g * 8 + 6], sv[g * 8 + 7]);
;                     const uint4 uu = {u0, u1, u2, u3};
;                     pf = __builtin_bit_cast(bf16x8, uu);
;                 }
;                 const int koff = (g >> 1) * 32 + (g & 1) * 16 + 8 * hh;
;                 const bf16x8 v0 = *(const bf16x8*)(sVt + ql * 72 + koff);
;                 const bf16x8 v1 = *(const bf16x8*)(sVt + (32 + ql) * 72 + koff);
;                 O0 = __builtin_amdgcn_mfma_f32_32x32x16_bf16(v0, pf, O0, 0, 0, 0);
;                 O1 = __builtin_amdgcn_mfma_f32_32x32x16_bf16(v1, pf, O1, 0, 0, 0);
.LBB0_113:
	s_or_b64 exec, exec, s[42:43]
	v_max_f32_e32 v40, v123, v123
	v_max_f32_e32 v41, v122, v122
	v_max_f32_e32 v40, v41, v40
	v_max3_f32 v40, v40, v120, v121
	v_max3_f32 v40, v40, v118, v119
	v_max3_f32 v40, v40, v54, v55
	v_max3_f32 v40, v40, v116, v117
	v_max3_f32 v40, v40, v50, v51
	v_max3_f32 v40, v40, v124, v125
	v_max3_f32 v40, v40, v60, v61
	v_max3_f32 v40, v40, v58, v59
	v_max3_f32 v40, v40, v52, v53
	v_max3_f32 v40, v40, v56, v57
	v_max3_f32 v40, v40, v48, v49
	v_max3_f32 v40, v40, v38, v39
	v_max3_f32 v40, v40, v34, v35
	v_cmp_lt_i32_e32 vcc, v133, v132
	v_max3_f32 v40, v40, v36, v37
	v_max3_f32 v40, v40, v32, v33
	v_cndmask_b32_e32 v41, v130, v133, vcc
	v_lshlrev_b32_e32 v41, 2, v41
	ds_bpermute_b32 v41, v41, v40
	s_waitcnt lgkmcnt(0)
	v_max_f32_e32 v42, v40, v41
	v_add_f32_e32 v43, 0xc3190000, v157
	v_cmp_lt_f32_e32 vcc, v42, v43
	s_andn2_b64 s[98:99], exec, vcc
	s_cbranch_scc0 .LBB0_114
	v_cmp_gt_f32_e32 vcc, v42, v157
	s_and_b64 s[98:99], exec, vcc
	v_max3_f32 v41, v157, v40, v41
	v_sub_f32_e32 v40, v122, v41
	v_exp_f32_e32 v62, v40
	v_sub_f32_e32 v40, v123, v41
	v_exp_f32_e32 v63, v40
	v_sub_f32_e32 v43, v120, v41
	v_exp_f32_e32 v120, v43
	v_sub_f32_e32 v43, v121, v41
	v_exp_f32_e32 v121, v43
	v_sub_f32_e32 v43, v118, v41
	v_add_f32_e32 v42, 0, v62
	v_exp_f32_e32 v118, v43
	v_sub_f32_e32 v43, v119, v41
	v_add_f32_e32 v42, v63, v42
	v_exp_f32_e32 v119, v43
	v_sub_f32_e32 v43, v54, v41
	v_add_f32_e32 v42, v120, v42
	v_exp_f32_e32 v122, v43
	v_sub_f32_e32 v43, v55, v41
	v_add_f32_e32 v42, v121, v42
	v_exp_f32_e32 v55, v43
	v_sub_f32_e32 v43, v116, v41
	v_add_f32_e32 v42, v118, v42
	v_exp_f32_e32 v116, v43
	v_sub_f32_e32 v43, v117, v41
	v_add_f32_e32 v42, v119, v42
	v_exp_f32_e32 v117, v43
	v_sub_f32_e32 v43, v50, v41
	v_add_f32_e32 v42, v122, v42
	v_exp_f32_e32 v123, v43
	v_sub_f32_e32 v43, v51, v41
	v_sub_f32_e32 v40, v157, v41
	v_add_f32_e32 v42, v55, v42
	v_exp_f32_e32 v157, v43
	v_sub_f32_e32 v43, v124, v41
	v_add_f32_e32 v42, v116, v42
	v_exp_f32_e32 v124, v43
	v_sub_f32_e32 v43, v125, v41
	v_add_f32_e32 v42, v117, v42
	v_exp_f32_e32 v125, v43
	v_add_f32_e32 v42, v123, v42
	v_add_f32_e32 v42, v157, v42
	v_add_f32_e32 v42, v124, v42
	v_add_f32_e32 v44, v125, v42
	v_sub_f32_e32 v42, v60, v41
	v_exp_f32_e32 v60, v42
	v_sub_f32_e32 v42, v61, v41
	v_exp_f32_e32 v61, v42
	v_sub_f32_e32 v42, v58, v41
	v_exp_f32_e32 v42, v42
	v_sub_f32_e32 v43, v59, v41
	v_exp_f32_e32 v43, v43
	v_add_f32_e32 v44, v60, v44
	v_add_f32_e32 v44, v61, v44
	v_add_f32_e32 v44, v42, v44
	v_add_f32_e32 v50, v43, v44
	v_sub_f32_e32 v44, v52, v41
	v_exp_f32_e32 v44, v44
	v_sub_f32_e32 v45, v53, v41
	v_exp_f32_e32 v45, v45
	v_sub_f32_e32 v46, v56, v41
	v_exp_f32_e32 v46, v46
	v_sub_f32_e32 v47, v57, v41
	v_exp_f32_e32 v47, v47
	v_add_f32_e32 v50, v44, v50
	v_add_f32_e32 v50, v45, v50
	v_sub_f32_e32 v48, v48, v41
	v_add_f32_e32 v50, v46, v50
	v_exp_f32_e32 v160, v48
	v_sub_f32_e32 v48, v49, v41
	v_add_f32_e32 v159, v47, v50
	v_exp_f32_e32 v161, v48
	ds_read_b64_tr_b16 v[48:49], v152 offset:9216
	ds_read_b64_tr_b16 v[50:51], v152 offset:9472
	ds_read_b64_tr_b16 v[56:57], v152 offset:13312
	ds_read_b64_tr_b16 v[58:59], v152 offset:13568
	v_exp_f32_e32 v40, v40
	v_cvt_pk_bf16_f32 v52, v62, v63
	v_cvt_pk_bf16_f32 v53, v120, v121
	v_cvt_pk_bf16_f32 v54, v118, v119
	v_cvt_pk_bf16_f32 v55, v122, v55
	v_sub_f32_e32 v38, v38, v41
	s_cmp_eq_u64 s[98:99], 0
	s_cbranch_scc1 .Lnr1a
	v_pk_mul_f32 v[14:15], v[14:15], v[40:41] op_sel_hi:[1,0]
	v_pk_mul_f32 v[12:13], v[12:13], v[40:41] op_sel_hi:[1,0]
	v_pk_mul_f32 v[10:11], v[10:11], v[40:41] op_sel_hi:[1,0]
	v_pk_mul_f32 v[8:9], v[8:9], v[40:41] op_sel_hi:[1,0]
	v_pk_mul_f32 v[6:7], v[6:7], v[40:41] op_sel_hi:[1,0]
	v_pk_mul_f32 v[4:5], v[4:5], v[40:41] op_sel_hi:[1,0]
	v_pk_mul_f32 v[2:3], v[2:3], v[40:41] op_sel_hi:[1,0]
	v_pk_mul_f32 v[0:1], v[0:1], v[40:41] op_sel_hi:[1,0]
	v_pk_mul_f32 v[30:31], v[30:31], v[40:41] op_sel_hi:[1,0]
	v_pk_mul_f32 v[28:29], v[28:29], v[40:41] op_sel_hi:[1,0]
; __device__ __forceinline__ unsigned pk_bf16(float lo, float hi) { unsigned r; asm("v_cvt_pk_bf16_f32 %0, %1, %2" : "=v"(r) : "v"(lo), "v"(hi)); return r; }
; __device__ void attn_item(const Params& p, int s_idx, char* smem) {
;     ...
;             for (int i = 0; i < 32; ++i) { sv[i] = __builtin_amdgcn_exp2f(sv[i] - mnew); psum += sv[i]; }
;             lsum = lsum * alpha + psum;
; #pragma unroll
;             for (int i = 0; i < 16; ++i) { O0[i] *= alpha; O1[i] *= alpha; }
; #pragma unroll
;             for (int g = 0; g < 4; ++g) {
;                 bf16x8 pf;
;                 {
;                     const unsigned u0 = pk_bf16(sv[g * 8 + 0], sv[g * 8 + 1]), u1 = pk_bf16(sv[g * 8 + 2], sv[g * 8 + 3]);
;                     const unsigned u2 = pk_bf16(sv[g * 8 + 4], sv[g * 8 + 5]), u3 = pk_bf16(sv[g * 8 + 6], sv[g * 8 + 7]);
;                     const uint4 uu = {u0, u1, u2, u3};
;                     pf = __builtin_bit_cast(bf16x8, uu);
;                 }
;                 const int koff = (g >> 1) * 32 + (g & 1) * 16 + 8 * hh;
;                 const bf16x8 v0 = *(const bf16x8*)(sVt + ql * 72 + koff);
;                 const bf16x8 v1 = *(const bf16x8*)(sVt + (32 + ql) * 72 + koff);
;                 O0 = __builtin_amdgcn_mfma_f32_32x32x16_bf16(v0, pf, O0, 0, 0, 0);
;                 O1 = __builtin_amdgcn_mfma_f32_32x32x16_bf16(v1, pf, O1, 0, 0, 0);
;             }
;         }
;     };
;     gload(0, sa); sstore(0, sa); __syncthreads();
;     for (int kt = 0; kt < nkt; kt += 2) {
;         gload(kt + 1, sa);
;         compute(kt, 0);
;         sstore(1, sa);
.Lnr1a:
	s_waitcnt lgkmcnt(2)
	v_mfma_f32_32x32x16_bf16 v[0:15], v[48:51], v[52:55], v[0:15]
	ds_read_b64_tr_b16 v[48:49], v152 offset:10240
	ds_read_b64_tr_b16 v[50:51], v152 offset:10496
	s_cmp_eq_u64 s[98:99], 0
	s_cbranch_scc1 .Lnr2a
	v_mul_f32_e64 v26, v26, v40
	v_mul_f32_e64 v27, v27, v40
	v_mul_f32_e64 v24, v24, v40
	v_mul_f32_e64 v25, v25, v40
	v_pk_mul_f32 v[22:23], v[22:23], v[40:41] op_sel_hi:[1,0]
	v_pk_mul_f32 v[20:21], v[20:21], v[40:41] op_sel_hi:[1,0]
	v_pk_mul_f32 v[18:19], v[18:19], v[40:41] op_sel_hi:[1,0]
	v_pk_mul_f32 v[16:17], v[16:17], v[40:41] op_sel_hi:[1,0]
.Lnr2a:
	v_exp_f32_e32 v38, v38
	v_sub_f32_e32 v39, v39, v41
	s_waitcnt lgkmcnt(2)
	v_mfma_f32_32x32x16_bf16 v[16:31], v[56:59], v[52:55], v[16:31]
	ds_read_b64_tr_b16 v[56:57], v152 offset:14336
	ds_read_b64_tr_b16 v[58:59], v152 offset:14592
	v_exp_f32_e32 v39, v39
	v_cvt_pk_bf16_f32 v52, v116, v117
	v_cvt_pk_bf16_f32 v53, v123, v157
	v_cvt_pk_bf16_f32 v54, v124, v125
	v_cvt_pk_bf16_f32 v55, v60, v61
	v_sub_f32_e32 v34, v34, v41
	s_waitcnt lgkmcnt(2)
	v_mfma_f32_32x32x16_bf16 v[0:15], v[48:51], v[52:55], v[0:15]
	v_add_f32_e32 v48, v160, v159
	v_add_f32_e32 v48, v161, v48
	v_add_f32_e32 v48, v38, v48
	v_add_f32_e32 v60, v39, v48
	ds_read_b64_tr_b16 v[48:49], v152 offset:11264
	ds_read_b64_tr_b16 v[50:51], v152 offset:11520
	v_exp_f32_e32 v61, v34
	v_sub_f32_e32 v34, v35, v41
	s_waitcnt lgkmcnt(2)
	v_mfma_f32_32x32x16_bf16 v[16:31], v[56:59], v[52:55], v[16:31]
	ds_read_b64_tr_b16 v[52:53], v152 offset:15360
	ds_read_b64_tr_b16 v[54:55], v152 offset:15616
	v_exp_f32_e32 v56, v34
	v_sub_f32_e32 v34, v36, v41
	v_cvt_pk_bf16_f32 v42, v42, v43
	v_cvt_pk_bf16_f32 v43, v44, v45
	v_cvt_pk_bf16_f32 v44, v46, v47
	v_cvt_pk_bf16_f32 v45, v160, v161
	v_sub_f32_e32 v32, v32, v41
	s_waitcnt lgkmcnt(2)
	v_mfma_f32_32x32x16_bf16 v[0:15], v[48:51], v[42:45], v[0:15]
	v_exp_f32_e32 v50, v34
	v_sub_f32_e32 v34, v37, v41
	v_exp_f32_e32 v51, v34
	ds_read_b64_tr_b16 v[34:35], v152 offset:12288
	ds_read_b64_tr_b16 v[36:37], v152 offset:12544
	ds_read_b64_tr_b16 v[46:47], v152 offset:16384
	ds_read_b64_tr_b16 v[48:49], v152 offset:16640
	v_sub_f32_e32 v33, v33, v41
	v_exp_f32_e32 v32, v32
	s_waitcnt lgkmcnt(4)
	v_mfma_f32_32x32x16_bf16 v[16:31], v[52:55], v[42:45], v[16:31]
	v_exp_f32_e32 v33, v33
	v_cvt_pk_bf16_f32 v42, v38, v39
	v_cvt_pk_bf16_f32 v43, v61, v56
	v_cvt_pk_bf16_f32 v44, v50, v51
	v_cvt_pk_bf16_f32 v45, v32, v33
	v_mov_b32_e32 v157, v41
	s_waitcnt lgkmcnt(2)
	v_mfma_f32_32x32x16_bf16 v[0:15], v[34:37], v[42:45], v[0:15]
	v_add_f32_e32 v34, v61, v60
	v_add_f32_e32 v34, v56, v34
	v_add_f32_e32 v34, v50, v34
	v_add_f32_e32 v34, v51, v34
	v_add_f32_e32 v32, v32, v34
	v_add_f32_e32 v32, v33, v32
	v_fmac_f32_e32 v32, v156, v40
	s_waitcnt lgkmcnt(0)
	v_mfma_f32_32x32x16_bf16 v[16:31], v[46:49], v[42:45], v[16:31]
	v_mov_b32_e32 v156, v32
.LBB0_114:
	s_or_b64 exec, exec, s[36:37]
	s_waitcnt vmcnt(4)
	ds_write_b128 v106, v[92:95] offset:18688
	s_waitcnt vmcnt(3)
	ds_write_b128 v107, v[84:87] offset:27904
	s_waitcnt vmcnt(2)
	ds_write_b128 v108, v[88:91] offset:18688
	s_waitcnt vmcnt(1)
	ds_write_b128 v109, v[80:83] offset:27904
	s_and_saveexec_b64 s[24:25], s[40:41]
	s_cbranch_execz .LBB0_116
	s_waitcnt vmcnt(0)
	ds_write_b32 v147, v158 offset:37120

; __device__ __forceinline__ unsigned pk_bf16(float lo, float hi) { unsigned r; asm("v_cvt_pk_bf16_f32 %0, %1, %2" : "=v"(r) : "v"(lo), "v"(hi)); return r; }
; __device__ void attn_item(const Params& p, int s_idx, char* smem) {
;     ...
;             float mx = sv[0];
; #pragma unroll
;             for (int i = 1; i < 32; ++i) mx = fmaxf(mx, sv[i]);
;             mx = fmaxf(mx, __shfl_xor(mx, 32));
;             const float mnew = fmaxf(mrun, mx);
;             const float alpha = __builtin_amdgcn_exp2f(mrun - mnew);
;             mrun = mnew;
;             float psum = 0.f;
; #pragma unroll
;             for (int i = 0; i < 32; ++i) { sv[i] = __builtin_amdgcn_exp2f(sv[i] - mnew); psum += sv[i]; }
;             lsum = lsum * alpha + psum;
; #pragma unroll
;             for (int i = 0; i < 16; ++i) { O0[i] *= alpha; O1[i] *= alpha; }
; #pragma unroll
;             for (int g = 0; g < 4; ++g) {
;                 bf16x8 pf;
;                 {
;                     const unsigned u0 = pk_bf16(sv[g * 8 + 0], sv[g * 8 + 1]), u1 = pk_bf16(sv[g * 8 + 2], sv[g * 8 + 3]);
;                     const unsigned u2 = pk_bf16(sv[g * 8 + 4], sv[g * 8 + 5]), u3 = pk_bf16(sv[g * 8 + 6], sv[g * 8 + 7]);
;                     const uint4 uu = {u0, u1, u2, u3};
;                     pf = __builtin_bit_cast(bf16x8, uu);
;                 }
;                 const int koff = (g >> 1) * 32 + (g & 1) * 16 + 8 * hh;
;                 const bf16x8 v0 = *(const bf16x8*)(sVt + ql * 72 + koff);
;                 const bf16x8 v1 = *(const bf16x8*)(sVt + (32 + ql) * 72 + koff);
;                 O0 = __builtin_amdgcn_mfma_f32_32x32x16_bf16(v0, pf, O0, 0, 0, 0);
;                 O1 = __builtin_amdgcn_mfma_f32_32x32x16_bf16(v1, pf, O1, 0, 0, 0);
.LBB0_119:
	s_or_b64 exec, exec, s[42:43]
	v_max_f32_e32 v40, v123, v123
	v_max_f32_e32 v41, v122, v122
	v_max_f32_e32 v40, v41, v40
	v_max3_f32 v40, v40, v120, v121
	v_max3_f32 v40, v40, v118, v119
	v_max3_f32 v40, v40, v54, v55
	v_max3_f32 v40, v40, v116, v117
	v_max3_f32 v40, v40, v50, v51
	v_max3_f32 v40, v40, v124, v125
	v_max3_f32 v40, v40, v60, v61
	v_max3_f32 v40, v40, v58, v59
	v_max3_f32 v40, v40, v52, v53
	v_max3_f32 v40, v40, v56, v57
	v_max3_f32 v40, v40, v48, v49
	v_max3_f32 v40, v40, v38, v39
	v_max3_f32 v40, v40, v34, v35
	v_cmp_lt_i32_e32 vcc, v133, v132
	v_max3_f32 v40, v40, v36, v37
	v_max3_f32 v40, v40, v32, v33
	v_cndmask_b32_e32 v41, v130, v133, vcc
	v_lshlrev_b32_e32 v41, 2, v41
	ds_bpermute_b32 v41, v41, v40
	s_waitcnt lgkmcnt(0)
	v_max_f32_e32 v42, v40, v41
	v_add_f32_e32 v43, 0xc3190000, v157
	v_cmp_lt_f32_e32 vcc, v42, v43
	s_andn2_b64 s[98:99], exec, vcc
	s_cbranch_scc0 .LBB0_120
	v_cmp_gt_f32_e32 vcc, v42, v157
	s_and_b64 s[98:99], exec, vcc
	v_max3_f32 v41, v157, v40, v41
	v_sub_f32_e32 v40, v122, v41
	v_exp_f32_e32 v62, v40
	v_sub_f32_e32 v40, v123, v41
	v_exp_f32_e32 v63, v40
	v_sub_f32_e32 v43, v120, v41
	v_exp_f32_e32 v120, v43
	v_sub_f32_e32 v43, v121, v41
	v_exp_f32_e32 v121, v43
	v_sub_f32_e32 v43, v118, v41
	v_add_f32_e32 v42, 0, v62
	v_exp_f32_e32 v118, v43
	v_sub_f32_e32 v43, v119, v41
	v_add_f32_e32 v42, v63, v42
	v_exp_f32_e32 v119, v43
	v_sub_f32_e32 v43, v54, v41
	v_add_f32_e32 v42, v120, v42
	v_exp_f32_e32 v122, v43
	v_sub_f32_e32 v43, v55, v41
	v_add_f32_e32 v42, v121, v42
	v_exp_f32_e32 v55, v43
	v_sub_f32_e32 v43, v116, v41
	v_add_f32_e32 v42, v118, v42
	v_exp_f32_e32 v116, v43
	v_sub_f32_e32 v43, v117, v41
	v_add_f32_e32 v42, v119, v42
	v_exp_f32_e32 v117, v43
	v_sub_f32_e32 v43, v50, v41
	v_add_f32_e32 v42, v122, v42
	v_exp_f32_e32 v123, v43
	v_sub_f32_e32 v43, v51, v41
	v_sub_f32_e32 v40, v157, v41
	v_add_f32_e32 v42, v55, v42
	v_exp_f32_e32 v157, v43
	v_sub_f32_e32 v43, v124, v41
	v_add_f32_e32 v42, v116, v42
	v_exp_f32_e32 v124, v43
	v_sub_f32_e32 v43, v125, v41
	v_add_f32_e32 v42, v117, v42
	v_exp_f32_e32 v125, v43
	v_add_f32_e32 v42, v123, v42
	v_add_f32_e32 v42, v157, v42
	v_add_f32_e32 v42, v124, v42
	v_add_f32_e32 v44, v125, v42
	v_sub_f32_e32 v42, v60, v41
	v_exp_f32_e32 v60, v42
	v_sub_f32_e32 v42, v61, v41
	v_exp_f32_e32 v61, v42
	v_sub_f32_e32 v42, v58, v41
	v_exp_f32_e32 v42, v42
	v_sub_f32_e32 v43, v59, v41
	v_exp_f32_e32 v43, v43
	v_add_f32_e32 v44, v60, v44
	v_add_f32_e32 v44, v61, v44
	v_add_f32_e32 v44, v42, v44
	v_add_f32_e32 v50, v43, v44
	v_sub_f32_e32 v44, v52, v41
	v_exp_f32_e32 v44, v44
	v_sub_f32_e32 v45, v53, v41
	v_exp_f32_e32 v45, v45
	v_sub_f32_e32 v46, v56, v41
	v_exp_f32_e32 v46, v46
	v_sub_f32_e32 v47, v57, v41
	v_exp_f32_e32 v47, v47
	v_add_f32_e32 v50, v44, v50
	v_add_f32_e32 v50, v45, v50
	v_sub_f32_e32 v48, v48, v41
	v_add_f32_e32 v50, v46, v50
	v_exp_f32_e32 v160, v48
	v_sub_f32_e32 v48, v49, v41
	v_add_f32_e32 v159, v47, v50
	v_exp_f32_e32 v161, v48
	ds_read_b64_tr_b16 v[48:49], v152 offset:27904
	ds_read_b64_tr_b16 v[50:51], v152 offset:28160
	ds_read_b64_tr_b16 v[56:57], v152 offset:32000
	ds_read_b64_tr_b16 v[58:59], v152 offset:32256
	v_exp_f32_e32 v40, v40
	v_cvt_pk_bf16_f32 v52, v62, v63
	v_cvt_pk_bf16_f32 v53, v120, v121
	v_cvt_pk_bf16_f32 v54, v118, v119
	v_cvt_pk_bf16_f32 v55, v122, v55
	v_sub_f32_e32 v38, v38, v41
	s_cmp_eq_u64 s[98:99], 0
	s_cbranch_scc1 .Lnr1b
	v_pk_mul_f32 v[14:15], v[14:15], v[40:41] op_sel_hi:[1,0]
	v_pk_mul_f32 v[12:13], v[12:13], v[40:41] op_sel_hi:[1,0]
	v_pk_mul_f32 v[10:11], v[10:11], v[40:41] op_sel_hi:[1,0]
	v_pk_mul_f32 v[8:9], v[8:9], v[40:41] op_sel_hi:[1,0]
	v_pk_mul_f32 v[6:7], v[6:7], v[40:41] op_sel_hi:[1,0]
	v_pk_mul_f32 v[4:5], v[4:5], v[40:41] op_sel_hi:[1,0]
	v_pk_mul_f32 v[2:3], v[2:3], v[40:41] op_sel_hi:[1,0]
	v_pk_mul_f32 v[0:1], v[0:1], v[40:41] op_sel_hi:[1,0]
	v_pk_mul_f32 v[30:31], v[30:31], v[40:41] op_sel_hi:[1,0]
	v_pk_mul_f32 v[28:29], v[28:29], v[40:41] op_sel_hi:[1,0]
; __device__ __forceinline__ unsigned pk_bf16(float lo, float hi) { unsigned r; asm("v_cvt_pk_bf16_f32 %0, %1, %2" : "=v"(r) : "v"(lo), "v"(hi)); return r; }
; __device__ void attn_item(const Params& p, int s_idx, char* smem) {
;     ...
; #pragma unroll
;             for (int i = 0; i < 16; ++i) { O0[i] *= alpha; O1[i] *= alpha; }
; #pragma unroll
;             for (int g = 0; g < 4; ++g) {
;                 bf16x8 pf;
;                 {
;                     const unsigned u0 = pk_bf16(sv[g * 8 + 0], sv[g * 8 + 1]), u1 = pk_bf16(sv[g * 8 + 2], sv[g * 8 + 3]);
;                     const unsigned u2 = pk_bf16(sv[g * 8 + 4], sv[g * 8 + 5]), u3 = pk_bf16(sv[g * 8 + 6], sv[g * 8 + 7]);
;                     const uint4 uu = {u0, u1, u2, u3};
;                     pf = __builtin_bit_cast(bf16x8, uu);
;                 }
;                 const int koff = (g >> 1) * 32 + (g & 1) * 16 + 8 * hh;
;                 const bf16x8 v0 = *(const bf16x8*)(sVt + ql * 72 + koff);
;                 const bf16x8 v1 = *(const bf16x8*)(sVt + (32 + ql) * 72 + koff);
;                 O0 = __builtin_amdgcn_mfma_f32_32x32x16_bf16(v0, pf, O0, 0, 0, 0);
;                 O1 = __builtin_amdgcn_mfma_f32_32x32x16_bf16(v1, pf, O1, 0, 0, 0);
;             }
;         }
;     };
;     gload(0, sa); sstore(0, sa); __syncthreads();
;     for (int kt = 0; kt < nkt; kt += 2) {
;         gload(kt + 1, sa);
;         compute(kt, 0);
;         sstore(1, sa);
;         __syncthreads();
;         gload(min(kt + 2, nkt - 1), sa);
;         compute(kt + 1, 1);
;         if (kt + 2 < nkt) sstore(0, sa);
.Lnr1b:
	s_waitcnt lgkmcnt(2)
	v_mfma_f32_32x32x16_bf16 v[0:15], v[48:51], v[52:55], v[0:15]
	ds_read_b64_tr_b16 v[48:49], v152 offset:28928
	ds_read_b64_tr_b16 v[50:51], v152 offset:29184
	s_cmp_eq_u64 s[98:99], 0
	s_cbranch_scc1 .Lnr2b
	v_mul_f32_e64 v26, v26, v40
	v_mul_f32_e64 v27, v27, v40
	v_mul_f32_e64 v24, v24, v40
	v_mul_f32_e64 v25, v25, v40
	v_pk_mul_f32 v[22:23], v[22:23], v[40:41] op_sel_hi:[1,0]
	v_pk_mul_f32 v[20:21], v[20:21], v[40:41] op_sel_hi:[1,0]
	v_pk_mul_f32 v[18:19], v[18:19], v[40:41] op_sel_hi:[1,0]
	v_pk_mul_f32 v[16:17], v[16:17], v[40:41] op_sel_hi:[1,0]
.Lnr2b:
	v_exp_f32_e32 v38, v38
	v_sub_f32_e32 v39, v39, v41
	s_waitcnt lgkmcnt(2)
	v_mfma_f32_32x32x16_bf16 v[16:31], v[56:59], v[52:55], v[16:31]
	ds_read_b64_tr_b16 v[56:57], v152 offset:33024
	ds_read_b64_tr_b16 v[58:59], v152 offset:33280
	v_exp_f32_e32 v39, v39
	v_cvt_pk_bf16_f32 v52, v116, v117
	v_cvt_pk_bf16_f32 v53, v123, v157
	v_cvt_pk_bf16_f32 v54, v124, v125
	v_cvt_pk_bf16_f32 v55, v60, v61
	v_sub_f32_e32 v34, v34, v41
	s_waitcnt lgkmcnt(2)
	v_mfma_f32_32x32x16_bf16 v[0:15], v[48:51], v[52:55], v[0:15]
	v_add_f32_e32 v48, v160, v159
	v_add_f32_e32 v48, v161, v48
	v_add_f32_e32 v48, v38, v48
	v_add_f32_e32 v60, v39, v48
	ds_read_b64_tr_b16 v[48:49], v152 offset:29952
	ds_read_b64_tr_b16 v[50:51], v152 offset:30208
	v_exp_f32_e32 v61, v34
	v_sub_f32_e32 v34, v35, v41
	s_waitcnt lgkmcnt(2)
	v_mfma_f32_32x32x16_bf16 v[16:31], v[56:59], v[52:55], v[16:31]
	ds_read_b64_tr_b16 v[52:53], v152 offset:34048
	ds_read_b64_tr_b16 v[54:55], v152 offset:34304
	v_exp_f32_e32 v56, v34
	v_sub_f32_e32 v34, v36, v41
	v_cvt_pk_bf16_f32 v42, v42, v43
	v_cvt_pk_bf16_f32 v43, v44, v45
	v_cvt_pk_bf16_f32 v44, v46, v47
	v_cvt_pk_bf16_f32 v45, v160, v161
	v_sub_f32_e32 v32, v32, v41
	s_waitcnt lgkmcnt(2)
	v_mfma_f32_32x32x16_bf16 v[0:15], v[48:51], v[42:45], v[0:15]
	v_exp_f32_e32 v50, v34
	v_sub_f32_e32 v34, v37, v41
	v_exp_f32_e32 v51, v34
	ds_read_b64_tr_b16 v[34:35], v152 offset:30976
	ds_read_b64_tr_b16 v[36:37], v152 offset:31232
	ds_read_b64_tr_b16 v[46:47], v152 offset:35072
	ds_read_b64_tr_b16 v[48:49], v152 offset:35328
	v_sub_f32_e32 v33, v33, v41
	v_exp_f32_e32 v32, v32
	s_waitcnt lgkmcnt(4)
	v_mfma_f32_32x32x16_bf16 v[16:31], v[52:55], v[42:45], v[16:31]
	v_exp_f32_e32 v33, v33
	v_cvt_pk_bf16_f32 v42, v38, v39
	v_cvt_pk_bf16_f32 v43, v61, v56
	v_cvt_pk_bf16_f32 v44, v50, v51
	v_cvt_pk_bf16_f32 v45, v32, v33
	v_mov_b32_e32 v157, v41
	s_waitcnt lgkmcnt(2)
	v_mfma_f32_32x32x16_bf16 v[0:15], v[34:37], v[42:45], v[0:15]
	v_add_f32_e32 v34, v61, v60
	v_add_f32_e32 v34, v56, v34
	v_add_f32_e32 v34, v50, v34
	v_add_f32_e32 v34, v51, v34
	v_add_f32_e32 v32, v32, v34
	v_add_f32_e32 v32, v33, v32
	v_fmac_f32_e32 v32, v156, v40
	s_waitcnt lgkmcnt(0)
	v_mfma_f32_32x32x16_bf16 v[16:31], v[46:49], v[42:45], v[16:31]
	v_mov_b32_e32 v156, v32
.LBB0_120:
	s_or_b64 exec, exec, s[36:37]
	s_cmp_le_u32 s16, 1
	s_cselect_b64 s[36:37], -1, 0
	s_and_b64 vcc, exec, s[36:37]
	s_cbranch_vccnz .LBB0_124
	s_waitcnt vmcnt(4)
	ds_write_b128 v106, v[92:95]
	s_waitcnt vmcnt(3)
	ds_write_b128 v107, v[84:87] offset:9216
	s_waitcnt vmcnt(2)
	ds_write_b128 v108, v[88:91]
	s_waitcnt vmcnt(1)
	ds_write_b128 v109, v[80:83] offset:9216
	s_and_saveexec_b64 s[24:25], s[40:41]
	s_cbranch_execz .LBB0_123
	s_waitcnt vmcnt(0)
	ds_write_b32 v147, v158 offset:18432
